# last M-tile (128 valid rows): waves whose rows lie beyond M only stage operands and keep the barrier cadence (no MFMA / fragment reads), valid waves get the SIMDs to themselves
# speedup vs baseline: 1.0787x; 1.0058x over previous
; DI void lds_barrier() { asm volatile("s_waitcnt lgkmcnt(0)\n\ts_barrier" ::: "memory"); }
; DI void gemm_run(const GemmCfg c, char* smem, float* const g_h, u16* const g_hb, float* const g_out, const int final_out) {
;     ...
;     int kt = 0;
;     for (; kt + 3 < nk; kt += 2) {
;       K_STEP(0, 1, kt + 2, true, true);
;       lds_barrier();
;       K_STEP(1, 0, kt + 3, true, true);
;       lds_barrier();
;     }
;     K_STEP(0, 1, 0, true, false);
;     lds_barrier();
;     K_STEP(1, 0, 0, false, false);
;     lds_barrier();
.Lgemm_disp_late:
	s_cmp_eq_u32 s78, 64
	s_cbranch_scc1 .Lgemm_kloop_idle
	s_cmp_eq_u32 s9, 0
	s_cbranch_scc1 .Lgemm_kloop_nl
	s_cmp_eq_u32 s9, 2
	s_cbranch_scc1 .Lgemm_kloop_r1e
	s_branch .LBB0_112

; DI void lds_barrier() { asm volatile("s_waitcnt lgkmcnt(0)\n\ts_barrier" ::: "memory"); }
; #define G_LOAD(RA, RB, KT) { size_t as_ = astep, bs_ = bstep; asm volatile("" : "+s"(as_), "+s"(bs_)); \
;       _Pragma("unroll") for (int i = 0; i < 4; ++i) { RA[i] = *(const u32x4*)(Ag + i * as_ + (KT) * 64); RB[i] = *(const u32x4*)(Bg + i * bs_ + (KT) * 64); } }
; DI void gemm_run(const GemmCfg c, char* smem, float* const g_h, u16* const g_hb, float* const g_out, const int final_out) {
;     ...
;     G_LOAD(ra0, rb0, 0);
;     __syncthreads();
;     G_STORE(ra0, rb0, 0);
;     G_LOAD(ra0, rb0, 1);
;     lds_barrier();
;     int kt = 0;
;     for (; kt + 3 < nk; kt += 2) {
;       K_STEP(0, 1, kt + 2, true, true);
;       lds_barrier();
;       K_STEP(1, 0, kt + 3, true, true);
;       lds_barrier();
;     }
.Lgemm_kloop_n:
	s_waitcnt lgkmcnt(8)
	v_mfma_f32_16x16x32_bf16 v[64:67], v[160:163], v[204:207], v[64:67]
	s_waitcnt lgkmcnt(7)
	v_mfma_f32_16x16x32_bf16 v[68:71], v[160:163], v[222:225], v[68:71]
	s_waitcnt lgkmcnt(6)
	v_mfma_f32_16x16x32_bf16 v[72:75], v[160:163], v[226:229], v[72:75]
	s_waitcnt lgkmcnt(5)
	v_mfma_f32_16x16x32_bf16 v[76:79], v[160:163], v[230:233], v[76:79]
	s_waitcnt lgkmcnt(4)
	v_mfma_f32_16x16x32_bf16 v[80:83], v[160:163], v[234:237], v[80:83]
	s_waitcnt lgkmcnt(3)
	v_mfma_f32_16x16x32_bf16 v[84:87], v[160:163], v[238:241], v[84:87]
	s_waitcnt lgkmcnt(2)
	v_mfma_f32_16x16x32_bf16 v[88:91], v[160:163], v[242:245], v[88:91]
	s_waitcnt lgkmcnt(1)
	v_mfma_f32_16x16x32_bf16 v[92:95], v[160:163], v[246:249], v[92:95]
	ds_read_b128 v[160:163], v215
	v_mfma_f32_16x16x32_bf16 v[96:99], v[176:179], v[204:207], v[96:99]
	v_mfma_f32_16x16x32_bf16 v[100:103], v[176:179], v[222:225], v[100:103]
	v_mfma_f32_16x16x32_bf16 v[104:107], v[176:179], v[226:229], v[104:107]
	v_mfma_f32_16x16x32_bf16 v[108:111], v[176:179], v[230:233], v[108:111]
	v_mfma_f32_16x16x32_bf16 v[112:115], v[176:179], v[234:237], v[112:115]
	v_mfma_f32_16x16x32_bf16 v[116:119], v[176:179], v[238:241], v[116:119]
	v_mfma_f32_16x16x32_bf16 v[120:123], v[176:179], v[242:245], v[120:123]
	v_mfma_f32_16x16x32_bf16 v[124:127], v[176:179], v[246:249], v[124:127]
	ds_read_b128 v[176:179], v215 offset:2048
	v_mfma_f32_16x16x32_bf16 v[0:3], v[180:183], v[204:207], v[0:3]
	v_mfma_f32_16x16x32_bf16 v[4:7], v[180:183], v[222:225], v[4:7]
	v_mfma_f32_16x16x32_bf16 v[8:11], v[180:183], v[226:229], v[8:11]
	v_mfma_f32_16x16x32_bf16 v[12:15], v[180:183], v[230:233], v[12:15]
	v_mfma_f32_16x16x32_bf16 v[16:19], v[180:183], v[234:237], v[16:19]
	v_mfma_f32_16x16x32_bf16 v[20:23], v[180:183], v[238:241], v[20:23]
	v_mfma_f32_16x16x32_bf16 v[24:27], v[180:183], v[242:245], v[24:27]
	v_mfma_f32_16x16x32_bf16 v[28:31], v[180:183], v[246:249], v[28:31]
	ds_read_b128 v[180:183], v215 offset:4096
	s_waitcnt lgkmcnt(3)
	v_mfma_f32_16x16x32_bf16 v[32:35], v[200:203], v[204:207], v[32:35]
	ds_read_b128 v[204:207], v197
	v_mfma_f32_16x16x32_bf16 v[36:39], v[200:203], v[222:225], v[36:39]
	ds_read_b128 v[222:225], v197 offset:2048
	v_mfma_f32_16x16x32_bf16 v[40:43], v[200:203], v[226:229], v[40:43]
	ds_read_b128 v[226:229], v197 offset:4096
	v_mfma_f32_16x16x32_bf16 v[44:47], v[200:203], v[230:233], v[44:47]
	ds_read_b128 v[230:233], v197 offset:6144
	v_mfma_f32_16x16x32_bf16 v[48:51], v[200:203], v[234:237], v[48:51]
	ds_read_b128 v[234:237], v197 offset:8192
	v_mfma_f32_16x16x32_bf16 v[52:55], v[200:203], v[238:241], v[52:55]
	ds_read_b128 v[238:241], v197 offset:10240
	v_mfma_f32_16x16x32_bf16 v[56:59], v[200:203], v[242:245], v[56:59]
	ds_read_b128 v[242:245], v197 offset:12288
	v_mfma_f32_16x16x32_bf16 v[60:63], v[200:203], v[246:249], v[60:63]
	ds_read_b128 v[246:249], v197 offset:14336
	ds_read_b128 v[200:203], v215 offset:6144
	s_waitcnt lgkmcnt(8)
	v_mfma_f32_16x16x32_bf16 v[64:67], v[160:163], v[204:207], v[64:67]
	s_waitcnt lgkmcnt(7)
	v_mfma_f32_16x16x32_bf16 v[68:71], v[160:163], v[222:225], v[68:71]
	s_waitcnt lgkmcnt(6)
	v_mfma_f32_16x16x32_bf16 v[72:75], v[160:163], v[226:229], v[72:75]
	s_waitcnt lgkmcnt(5)
	v_mfma_f32_16x16x32_bf16 v[76:79], v[160:163], v[230:233], v[76:79]
	s_waitcnt lgkmcnt(4)
	v_mfma_f32_16x16x32_bf16 v[80:83], v[160:163], v[234:237], v[80:83]
	s_waitcnt lgkmcnt(3)
	v_mfma_f32_16x16x32_bf16 v[84:87], v[160:163], v[238:241], v[84:87]
	s_waitcnt lgkmcnt(2)
	v_mfma_f32_16x16x32_bf16 v[88:91], v[160:163], v[242:245], v[88:91]
	s_waitcnt lgkmcnt(1)
	v_mfma_f32_16x16x32_bf16 v[92:95], v[160:163], v[246:249], v[92:95]
	s_waitcnt vmcnt(0) lgkmcnt(0)
	s_barrier
	s_add_u32 m0, s8, 0x0
	ds_read_b128 v[160:163], v194 offset:36864
	v_mfma_f32_16x16x32_bf16 v[96:99], v[176:179], v[204:207], v[96:99]
	global_load_lds_dwordx4 v130, s[4:5]
	s_add_u32 m0, s8, 0x12000
	v_mfma_f32_16x16x32_bf16 v[100:103], v[176:179], v[222:225], v[100:103]
	global_load_lds_dwordx4 v134, s[6:7]
	s_add_u32 m0, s8, 0x400
	v_mfma_f32_16x16x32_bf16 v[104:107], v[176:179], v[226:229], v[104:107]
	global_load_lds_dwordx4 v131, s[4:5]
	s_add_u32 m0, s8, 0x12400
	v_mfma_f32_16x16x32_bf16 v[108:111], v[176:179], v[230:233], v[108:111]
	global_load_lds_dwordx4 v135, s[6:7]
	s_add_u32 m0, s8, 0x800
	v_mfma_f32_16x16x32_bf16 v[112:115], v[176:179], v[234:237], v[112:115]
	global_load_lds_dwordx4 v132, s[4:5]
	s_add_u32 m0, s8, 0x12800
	v_mfma_f32_16x16x32_bf16 v[116:119], v[176:179], v[238:241], v[116:119]
	global_load_lds_dwordx4 v136, s[6:7]
	s_add_u32 m0, s8, 0xc00
	v_mfma_f32_16x16x32_bf16 v[120:123], v[176:179], v[242:245], v[120:123]
	global_load_lds_dwordx4 v133, s[4:5]
	s_add_u32 m0, s8, 0x12c00
	v_mfma_f32_16x16x32_bf16 v[124:127], v[176:179], v[246:249], v[124:127]
	global_load_lds_dwordx4 v137, s[6:7]
	ds_read_b128 v[176:179], v194 offset:38912
	v_mfma_f32_16x16x32_bf16 v[0:3], v[180:183], v[204:207], v[0:3]
	s_add_u32 s4, s4, 0x80
	s_addc_u32 s5, s5, 0
	s_add_u32 s6, s6, 0x80
	s_addc_u32 s7, s7, 0
	v_mfma_f32_16x16x32_bf16 v[4:7], v[180:183], v[222:225], v[4:7]
	v_mfma_f32_16x16x32_bf16 v[8:11], v[180:183], v[226:229], v[8:11]
	v_mfma_f32_16x16x32_bf16 v[12:15], v[180:183], v[230:233], v[12:15]
	v_mfma_f32_16x16x32_bf16 v[16:19], v[180:183], v[234:237], v[16:19]
	v_mfma_f32_16x16x32_bf16 v[20:23], v[180:183], v[238:241], v[20:23]
	v_mfma_f32_16x16x32_bf16 v[24:27], v[180:183], v[242:245], v[24:27]
	v_mfma_f32_16x16x32_bf16 v[28:31], v[180:183], v[246:249], v[28:31]
	ds_read_b128 v[180:183], v194 offset:40960
	v_mfma_f32_16x16x32_bf16 v[32:35], v[200:203], v[204:207], v[32:35]
	ds_read_b128 v[204:207], v195 offset:36864
	v_mfma_f32_16x16x32_bf16 v[36:39], v[200:203], v[222:225], v[36:39]
	ds_read_b128 v[222:225], v195 offset:38912
	v_mfma_f32_16x16x32_bf16 v[40:43], v[200:203], v[226:229], v[40:43]
	ds_read_b128 v[226:229], v195 offset:40960
	v_mfma_f32_16x16x32_bf16 v[44:47], v[200:203], v[230:233], v[44:47]
	ds_read_b128 v[230:233], v195 offset:43008
	v_mfma_f32_16x16x32_bf16 v[48:51], v[200:203], v[234:237], v[48:51]
	ds_read_b128 v[234:237], v195 offset:45056
	v_mfma_f32_16x16x32_bf16 v[52:55], v[200:203], v[238:241], v[52:55]
	ds_read_b128 v[238:241], v195 offset:47104
	v_mfma_f32_16x16x32_bf16 v[56:59], v[200:203], v[242:245], v[56:59]
	ds_read_b128 v[242:245], v195 offset:49152
	v_mfma_f32_16x16x32_bf16 v[60:63], v[200:203], v[246:249], v[60:63]
	ds_read_b128 v[246:249], v195 offset:51200
	ds_read_b128 v[200:203], v194 offset:43008
	s_waitcnt lgkmcnt(8)
; DI void lds_barrier() { asm volatile("s_waitcnt lgkmcnt(0)\n\ts_barrier" ::: "memory"); }
; #define G_LOAD(RA, RB, KT) { size_t as_ = astep, bs_ = bstep; asm volatile("" : "+s"(as_), "+s"(bs_)); \
;       _Pragma("unroll") for (int i = 0; i < 4; ++i) { RA[i] = *(const u32x4*)(Ag + i * as_ + (KT) * 64); RB[i] = *(const u32x4*)(Bg + i * bs_ + (KT) * 64); } }
; DI void gemm_run(const GemmCfg c, char* smem, float* const g_h, u16* const g_hb, float* const g_out, const int final_out) {
;     ...
;     G_LOAD(ra0, rb0, 0);
;     __syncthreads();
;     G_STORE(ra0, rb0, 0);
;     G_LOAD(ra0, rb0, 1);
;     lds_barrier();
;     int kt = 0;
;     for (; kt + 3 < nk; kt += 2) {
;       K_STEP(0, 1, kt + 2, true, true);
;       lds_barrier();
;       K_STEP(1, 0, kt + 3, true, true);
;       lds_barrier();
;     }
	v_mfma_f32_16x16x32_bf16 v[64:67], v[160:163], v[204:207], v[64:67]
	s_waitcnt lgkmcnt(7)
	v_mfma_f32_16x16x32_bf16 v[68:71], v[160:163], v[222:225], v[68:71]
	s_waitcnt lgkmcnt(6)
	v_mfma_f32_16x16x32_bf16 v[72:75], v[160:163], v[226:229], v[72:75]
	s_waitcnt lgkmcnt(5)
	v_mfma_f32_16x16x32_bf16 v[76:79], v[160:163], v[230:233], v[76:79]
	s_waitcnt lgkmcnt(4)
	v_mfma_f32_16x16x32_bf16 v[80:83], v[160:163], v[234:237], v[80:83]
	s_waitcnt lgkmcnt(3)
	v_mfma_f32_16x16x32_bf16 v[84:87], v[160:163], v[238:241], v[84:87]
	s_waitcnt lgkmcnt(2)
	v_mfma_f32_16x16x32_bf16 v[88:91], v[160:163], v[242:245], v[88:91]
	s_waitcnt lgkmcnt(1)
	v_mfma_f32_16x16x32_bf16 v[92:95], v[160:163], v[246:249], v[92:95]
	ds_read_b128 v[160:163], v215 offset:36864
	v_mfma_f32_16x16x32_bf16 v[96:99], v[176:179], v[204:207], v[96:99]
	v_mfma_f32_16x16x32_bf16 v[100:103], v[176:179], v[222:225], v[100:103]
	v_mfma_f32_16x16x32_bf16 v[104:107], v[176:179], v[226:229], v[104:107]
	v_mfma_f32_16x16x32_bf16 v[108:111], v[176:179], v[230:233], v[108:111]
	v_mfma_f32_16x16x32_bf16 v[112:115], v[176:179], v[234:237], v[112:115]
	v_mfma_f32_16x16x32_bf16 v[116:119], v[176:179], v[238:241], v[116:119]
	v_mfma_f32_16x16x32_bf16 v[120:123], v[176:179], v[242:245], v[120:123]
	v_mfma_f32_16x16x32_bf16 v[124:127], v[176:179], v[246:249], v[124:127]
	ds_read_b128 v[176:179], v215 offset:38912
	v_mfma_f32_16x16x32_bf16 v[0:3], v[180:183], v[204:207], v[0:3]
	v_mfma_f32_16x16x32_bf16 v[4:7], v[180:183], v[222:225], v[4:7]
	v_mfma_f32_16x16x32_bf16 v[8:11], v[180:183], v[226:229], v[8:11]
	v_mfma_f32_16x16x32_bf16 v[12:15], v[180:183], v[230:233], v[12:15]
	v_mfma_f32_16x16x32_bf16 v[16:19], v[180:183], v[234:237], v[16:19]
	v_mfma_f32_16x16x32_bf16 v[20:23], v[180:183], v[238:241], v[20:23]
	v_mfma_f32_16x16x32_bf16 v[24:27], v[180:183], v[242:245], v[24:27]
	v_mfma_f32_16x16x32_bf16 v[28:31], v[180:183], v[246:249], v[28:31]
	ds_read_b128 v[180:183], v215 offset:40960
	s_waitcnt lgkmcnt(3)
	v_mfma_f32_16x16x32_bf16 v[32:35], v[200:203], v[204:207], v[32:35]
	ds_read_b128 v[204:207], v197 offset:36864
	v_mfma_f32_16x16x32_bf16 v[36:39], v[200:203], v[222:225], v[36:39]
	ds_read_b128 v[222:225], v197 offset:38912
	v_mfma_f32_16x16x32_bf16 v[40:43], v[200:203], v[226:229], v[40:43]
	ds_read_b128 v[226:229], v197 offset:40960
	v_mfma_f32_16x16x32_bf16 v[44:47], v[200:203], v[230:233], v[44:47]
	ds_read_b128 v[230:233], v197 offset:43008
	v_mfma_f32_16x16x32_bf16 v[48:51], v[200:203], v[234:237], v[48:51]
	ds_read_b128 v[234:237], v197 offset:45056
	v_mfma_f32_16x16x32_bf16 v[52:55], v[200:203], v[238:241], v[52:55]
	ds_read_b128 v[238:241], v197 offset:47104
	v_mfma_f32_16x16x32_bf16 v[56:59], v[200:203], v[242:245], v[56:59]
	ds_read_b128 v[242:245], v197 offset:49152
	v_mfma_f32_16x16x32_bf16 v[60:63], v[200:203], v[246:249], v[60:63]
	ds_read_b128 v[246:249], v197 offset:51200
	ds_read_b128 v[200:203], v215 offset:43008
	s_waitcnt lgkmcnt(8)
	v_mfma_f32_16x16x32_bf16 v[64:67], v[160:163], v[204:207], v[64:67]
	s_waitcnt lgkmcnt(7)
	v_mfma_f32_16x16x32_bf16 v[68:71], v[160:163], v[222:225], v[68:71]
	s_waitcnt lgkmcnt(6)
	v_mfma_f32_16x16x32_bf16 v[72:75], v[160:163], v[226:229], v[72:75]
	s_waitcnt lgkmcnt(5)
	v_mfma_f32_16x16x32_bf16 v[76:79], v[160:163], v[230:233], v[76:79]
	s_waitcnt lgkmcnt(4)
	v_mfma_f32_16x16x32_bf16 v[80:83], v[160:163], v[234:237], v[80:83]
	s_waitcnt lgkmcnt(3)
	v_mfma_f32_16x16x32_bf16 v[84:87], v[160:163], v[238:241], v[84:87]
	s_waitcnt lgkmcnt(2)
	v_mfma_f32_16x16x32_bf16 v[88:91], v[160:163], v[242:245], v[88:91]
	s_waitcnt lgkmcnt(1)
	v_mfma_f32_16x16x32_bf16 v[92:95], v[160:163], v[246:249], v[92:95]
	s_waitcnt vmcnt(0) lgkmcnt(0)
	s_barrier
	s_add_u32 m0, s8, 0x9000
	ds_read_b128 v[160:163], v194
	v_mfma_f32_16x16x32_bf16 v[96:99], v[176:179], v[204:207], v[96:99]
	global_load_lds_dwordx4 v130, s[4:5]
	s_add_u32 m0, s8, 0x1b000
	v_mfma_f32_16x16x32_bf16 v[100:103], v[176:179], v[222:225], v[100:103]
	global_load_lds_dwordx4 v134, s[6:7]
	s_add_u32 m0, s8, 0x9400
	v_mfma_f32_16x16x32_bf16 v[104:107], v[176:179], v[226:229], v[104:107]
	global_load_lds_dwordx4 v131, s[4:5]
	s_add_u32 m0, s8, 0x1b400
	v_mfma_f32_16x16x32_bf16 v[108:111], v[176:179], v[230:233], v[108:111]
	global_load_lds_dwordx4 v135, s[6:7]
	s_add_u32 m0, s8, 0x9800
	v_mfma_f32_16x16x32_bf16 v[112:115], v[176:179], v[234:237], v[112:115]
	global_load_lds_dwordx4 v132, s[4:5]
	s_add_u32 m0, s8, 0x1b800
	v_mfma_f32_16x16x32_bf16 v[116:119], v[176:179], v[238:241], v[116:119]
	global_load_lds_dwordx4 v136, s[6:7]
	s_add_u32 m0, s8, 0x9c00
	v_mfma_f32_16x16x32_bf16 v[120:123], v[176:179], v[242:245], v[120:123]
	global_load_lds_dwordx4 v133, s[4:5]
	s_add_u32 m0, s8, 0x1bc00
	v_mfma_f32_16x16x32_bf16 v[124:127], v[176:179], v[246:249], v[124:127]
	global_load_lds_dwordx4 v137, s[6:7]
	ds_read_b128 v[176:179], v194 offset:2048
	v_mfma_f32_16x16x32_bf16 v[0:3], v[180:183], v[204:207], v[0:3]
	s_add_u32 s4, s4, 0x80
	s_addc_u32 s5, s5, 0
	s_add_u32 s6, s6, 0x80
	s_addc_u32 s7, s7, 0
	v_mfma_f32_16x16x32_bf16 v[4:7], v[180:183], v[222:225], v[4:7]
	v_mfma_f32_16x16x32_bf16 v[8:11], v[180:183], v[226:229], v[8:11]
	v_mfma_f32_16x16x32_bf16 v[12:15], v[180:183], v[230:233], v[12:15]
	v_mfma_f32_16x16x32_bf16 v[16:19], v[180:183], v[234:237], v[16:19]
	v_mfma_f32_16x16x32_bf16 v[20:23], v[180:183], v[238:241], v[20:23]
	v_mfma_f32_16x16x32_bf16 v[24:27], v[180:183], v[242:245], v[24:27]
	v_mfma_f32_16x16x32_bf16 v[28:31], v[180:183], v[246:249], v[28:31]
	ds_read_b128 v[180:183], v194 offset:4096
	v_mfma_f32_16x16x32_bf16 v[32:35], v[200:203], v[204:207], v[32:35]
	ds_read_b128 v[204:207], v195
	v_mfma_f32_16x16x32_bf16 v[36:39], v[200:203], v[222:225], v[36:39]
	ds_read_b128 v[222:225], v195 offset:2048
	v_mfma_f32_16x16x32_bf16 v[40:43], v[200:203], v[226:229], v[40:43]
	ds_read_b128 v[226:229], v195 offset:4096
	v_mfma_f32_16x16x32_bf16 v[44:47], v[200:203], v[230:233], v[44:47]
	ds_read_b128 v[230:233], v195 offset:6144
	v_mfma_f32_16x16x32_bf16 v[48:51], v[200:203], v[234:237], v[48:51]
	ds_read_b128 v[234:237], v195 offset:8192
	v_mfma_f32_16x16x32_bf16 v[52:55], v[200:203], v[238:241], v[52:55]
	ds_read_b128 v[238:241], v195 offset:10240
	v_mfma_f32_16x16x32_bf16 v[56:59], v[200:203], v[242:245], v[56:59]
	ds_read_b128 v[242:245], v195 offset:12288
	v_mfma_f32_16x16x32_bf16 v[60:63], v[200:203], v[246:249], v[60:63]
	ds_read_b128 v[246:249], v195 offset:14336
	ds_read_b128 v[200:203], v194 offset:6144
	s_add_i32 s1, s1, 2
	s_cmp_lt_i32 s1, s0
	s_cbranch_scc1 .Lgemm_kloop_n
; DI void lds_barrier() { asm volatile("s_waitcnt lgkmcnt(0)\n\ts_barrier" ::: "memory"); }
; DI void gemm_run(const GemmCfg c, char* smem, float* const g_h, u16* const g_hb, float* const g_out, const int final_out) {
;     ...
;     for (; kt + 3 < nk; kt += 2) {
;       K_STEP(0, 1, kt + 2, true, true);
;       lds_barrier();
;       K_STEP(1, 0, kt + 3, true, true);
;       lds_barrier();
;     }
;     K_STEP(0, 1, 0, true, false);
;     lds_barrier();
;     K_STEP(1, 0, 0, false, false);
;     lds_barrier();
	s_waitcnt lgkmcnt(8)
	v_mfma_f32_16x16x32_bf16 v[64:67], v[160:163], v[204:207], v[64:67]
	s_waitcnt lgkmcnt(7)
	v_mfma_f32_16x16x32_bf16 v[68:71], v[160:163], v[222:225], v[68:71]
	s_waitcnt lgkmcnt(6)
	v_mfma_f32_16x16x32_bf16 v[72:75], v[160:163], v[226:229], v[72:75]
	s_waitcnt lgkmcnt(5)
	v_mfma_f32_16x16x32_bf16 v[76:79], v[160:163], v[230:233], v[76:79]
	s_waitcnt lgkmcnt(4)
	v_mfma_f32_16x16x32_bf16 v[80:83], v[160:163], v[234:237], v[80:83]
	s_waitcnt lgkmcnt(3)
	v_mfma_f32_16x16x32_bf16 v[84:87], v[160:163], v[238:241], v[84:87]
	s_waitcnt lgkmcnt(2)
	v_mfma_f32_16x16x32_bf16 v[88:91], v[160:163], v[242:245], v[88:91]
	s_waitcnt lgkmcnt(1)
	v_mfma_f32_16x16x32_bf16 v[92:95], v[160:163], v[246:249], v[92:95]
	ds_read_b128 v[160:163], v215
	v_mfma_f32_16x16x32_bf16 v[96:99], v[176:179], v[204:207], v[96:99]
	v_mfma_f32_16x16x32_bf16 v[100:103], v[176:179], v[222:225], v[100:103]
	v_mfma_f32_16x16x32_bf16 v[104:107], v[176:179], v[226:229], v[104:107]
	v_mfma_f32_16x16x32_bf16 v[108:111], v[176:179], v[230:233], v[108:111]
	v_mfma_f32_16x16x32_bf16 v[112:115], v[176:179], v[234:237], v[112:115]
	v_mfma_f32_16x16x32_bf16 v[116:119], v[176:179], v[238:241], v[116:119]
	v_mfma_f32_16x16x32_bf16 v[120:123], v[176:179], v[242:245], v[120:123]
	v_mfma_f32_16x16x32_bf16 v[124:127], v[176:179], v[246:249], v[124:127]
	ds_read_b128 v[176:179], v215 offset:2048
	v_mfma_f32_16x16x32_bf16 v[0:3], v[180:183], v[204:207], v[0:3]
	v_mfma_f32_16x16x32_bf16 v[4:7], v[180:183], v[222:225], v[4:7]
	v_mfma_f32_16x16x32_bf16 v[8:11], v[180:183], v[226:229], v[8:11]
	v_mfma_f32_16x16x32_bf16 v[12:15], v[180:183], v[230:233], v[12:15]
	v_mfma_f32_16x16x32_bf16 v[16:19], v[180:183], v[234:237], v[16:19]
	v_mfma_f32_16x16x32_bf16 v[20:23], v[180:183], v[238:241], v[20:23]
	v_mfma_f32_16x16x32_bf16 v[24:27], v[180:183], v[242:245], v[24:27]
	v_mfma_f32_16x16x32_bf16 v[28:31], v[180:183], v[246:249], v[28:31]
	ds_read_b128 v[180:183], v215 offset:4096
	s_waitcnt lgkmcnt(3)
	v_mfma_f32_16x16x32_bf16 v[32:35], v[200:203], v[204:207], v[32:35]
	ds_read_b128 v[204:207], v197
	v_mfma_f32_16x16x32_bf16 v[36:39], v[200:203], v[222:225], v[36:39]
	ds_read_b128 v[222:225], v197 offset:2048
	v_mfma_f32_16x16x32_bf16 v[40:43], v[200:203], v[226:229], v[40:43]
	ds_read_b128 v[226:229], v197 offset:4096
	v_mfma_f32_16x16x32_bf16 v[44:47], v[200:203], v[230:233], v[44:47]
	ds_read_b128 v[230:233], v197 offset:6144
	v_mfma_f32_16x16x32_bf16 v[48:51], v[200:203], v[234:237], v[48:51]
	ds_read_b128 v[234:237], v197 offset:8192
	v_mfma_f32_16x16x32_bf16 v[52:55], v[200:203], v[238:241], v[52:55]
	ds_read_b128 v[238:241], v197 offset:10240
	v_mfma_f32_16x16x32_bf16 v[56:59], v[200:203], v[242:245], v[56:59]
	ds_read_b128 v[242:245], v197 offset:12288
	v_mfma_f32_16x16x32_bf16 v[60:63], v[200:203], v[246:249], v[60:63]
	ds_read_b128 v[246:249], v197 offset:14336
	ds_read_b128 v[200:203], v215 offset:6144
	s_waitcnt lgkmcnt(8)
	v_mfma_f32_16x16x32_bf16 v[64:67], v[160:163], v[204:207], v[64:67]
	s_waitcnt lgkmcnt(7)
	v_mfma_f32_16x16x32_bf16 v[68:71], v[160:163], v[222:225], v[68:71]
	s_waitcnt lgkmcnt(6)
	v_mfma_f32_16x16x32_bf16 v[72:75], v[160:163], v[226:229], v[72:75]
	s_waitcnt lgkmcnt(5)
	v_mfma_f32_16x16x32_bf16 v[76:79], v[160:163], v[230:233], v[76:79]
	s_waitcnt lgkmcnt(4)
	v_mfma_f32_16x16x32_bf16 v[80:83], v[160:163], v[234:237], v[80:83]
	s_waitcnt lgkmcnt(3)
	v_mfma_f32_16x16x32_bf16 v[84:87], v[160:163], v[238:241], v[84:87]
	s_waitcnt lgkmcnt(2)
	v_mfma_f32_16x16x32_bf16 v[88:91], v[160:163], v[242:245], v[88:91]
	s_waitcnt lgkmcnt(1)
	v_mfma_f32_16x16x32_bf16 v[92:95], v[160:163], v[246:249], v[92:95]
	s_waitcnt vmcnt(0) lgkmcnt(0)
	s_barrier
	ds_read_b128 v[160:163], v194 offset:36864
	v_mfma_f32_16x16x32_bf16 v[96:99], v[176:179], v[204:207], v[96:99]
	v_mfma_f32_16x16x32_bf16 v[100:103], v[176:179], v[222:225], v[100:103]
	v_mfma_f32_16x16x32_bf16 v[104:107], v[176:179], v[226:229], v[104:107]
	v_mfma_f32_16x16x32_bf16 v[108:111], v[176:179], v[230:233], v[108:111]
	v_mfma_f32_16x16x32_bf16 v[112:115], v[176:179], v[234:237], v[112:115]
	v_mfma_f32_16x16x32_bf16 v[116:119], v[176:179], v[238:241], v[116:119]
	v_mfma_f32_16x16x32_bf16 v[120:123], v[176:179], v[242:245], v[120:123]
	v_mfma_f32_16x16x32_bf16 v[124:127], v[176:179], v[246:249], v[124:127]
	ds_read_b128 v[176:179], v194 offset:38912
	v_mfma_f32_16x16x32_bf16 v[0:3], v[180:183], v[204:207], v[0:3]
	v_mfma_f32_16x16x32_bf16 v[4:7], v[180:183], v[222:225], v[4:7]
	v_mfma_f32_16x16x32_bf16 v[8:11], v[180:183], v[226:229], v[8:11]
	v_mfma_f32_16x16x32_bf16 v[12:15], v[180:183], v[230:233], v[12:15]
	v_mfma_f32_16x16x32_bf16 v[16:19], v[180:183], v[234:237], v[16:19]
	v_mfma_f32_16x16x32_bf16 v[20:23], v[180:183], v[238:241], v[20:23]
	v_mfma_f32_16x16x32_bf16 v[24:27], v[180:183], v[242:245], v[24:27]
	v_mfma_f32_16x16x32_bf16 v[28:31], v[180:183], v[246:249], v[28:31]
	ds_read_b128 v[180:183], v194 offset:40960
	v_mfma_f32_16x16x32_bf16 v[32:35], v[200:203], v[204:207], v[32:35]
	ds_read_b128 v[204:207], v195 offset:36864
	v_mfma_f32_16x16x32_bf16 v[36:39], v[200:203], v[222:225], v[36:39]
	ds_read_b128 v[222:225], v195 offset:38912
	v_mfma_f32_16x16x32_bf16 v[40:43], v[200:203], v[226:229], v[40:43]
	ds_read_b128 v[226:229], v195 offset:40960
	v_mfma_f32_16x16x32_bf16 v[44:47], v[200:203], v[230:233], v[44:47]
	ds_read_b128 v[230:233], v195 offset:43008
	v_mfma_f32_16x16x32_bf16 v[48:51], v[200:203], v[234:237], v[48:51]
	ds_read_b128 v[234:237], v195 offset:45056
	v_mfma_f32_16x16x32_bf16 v[52:55], v[200:203], v[238:241], v[52:55]
	ds_read_b128 v[238:241], v195 offset:47104
	v_mfma_f32_16x16x32_bf16 v[56:59], v[200:203], v[242:245], v[56:59]
	ds_read_b128 v[242:245], v195 offset:49152
	v_mfma_f32_16x16x32_bf16 v[60:63], v[200:203], v[246:249], v[60:63]
	ds_read_b128 v[246:249], v195 offset:51200
	ds_read_b128 v[200:203], v194 offset:43008
	s_waitcnt lgkmcnt(8)
; DI void lds_barrier() { asm volatile("s_waitcnt lgkmcnt(0)\n\ts_barrier" ::: "memory"); }
; DI void gemm_run(const GemmCfg c, char* smem, float* const g_h, u16* const g_hb, float* const g_out, const int final_out) {
;     ...
;     for (; kt + 3 < nk; kt += 2) {
;       K_STEP(0, 1, kt + 2, true, true);
;       lds_barrier();
;       K_STEP(1, 0, kt + 3, true, true);
;       lds_barrier();
;     }
;     K_STEP(0, 1, 0, true, false);
;     lds_barrier();
;     K_STEP(1, 0, 0, false, false);
;     lds_barrier();
	v_mfma_f32_16x16x32_bf16 v[64:67], v[160:163], v[204:207], v[64:67]
	s_waitcnt lgkmcnt(7)
	v_mfma_f32_16x16x32_bf16 v[68:71], v[160:163], v[222:225], v[68:71]
	s_waitcnt lgkmcnt(6)
	v_mfma_f32_16x16x32_bf16 v[72:75], v[160:163], v[226:229], v[72:75]
	s_waitcnt lgkmcnt(5)
	v_mfma_f32_16x16x32_bf16 v[76:79], v[160:163], v[230:233], v[76:79]
	s_waitcnt lgkmcnt(4)
	v_mfma_f32_16x16x32_bf16 v[80:83], v[160:163], v[234:237], v[80:83]
	s_waitcnt lgkmcnt(3)
	v_mfma_f32_16x16x32_bf16 v[84:87], v[160:163], v[238:241], v[84:87]
	s_waitcnt lgkmcnt(2)
	v_mfma_f32_16x16x32_bf16 v[88:91], v[160:163], v[242:245], v[88:91]
	s_waitcnt lgkmcnt(1)
	v_mfma_f32_16x16x32_bf16 v[92:95], v[160:163], v[246:249], v[92:95]
	ds_read_b128 v[160:163], v215 offset:36864
	v_mfma_f32_16x16x32_bf16 v[96:99], v[176:179], v[204:207], v[96:99]
	v_mfma_f32_16x16x32_bf16 v[100:103], v[176:179], v[222:225], v[100:103]
	v_mfma_f32_16x16x32_bf16 v[104:107], v[176:179], v[226:229], v[104:107]
	v_mfma_f32_16x16x32_bf16 v[108:111], v[176:179], v[230:233], v[108:111]
	v_mfma_f32_16x16x32_bf16 v[112:115], v[176:179], v[234:237], v[112:115]
	v_mfma_f32_16x16x32_bf16 v[116:119], v[176:179], v[238:241], v[116:119]
	v_mfma_f32_16x16x32_bf16 v[120:123], v[176:179], v[242:245], v[120:123]
	v_mfma_f32_16x16x32_bf16 v[124:127], v[176:179], v[246:249], v[124:127]
	ds_read_b128 v[176:179], v215 offset:38912
	v_mfma_f32_16x16x32_bf16 v[0:3], v[180:183], v[204:207], v[0:3]
	v_mfma_f32_16x16x32_bf16 v[4:7], v[180:183], v[222:225], v[4:7]
	v_mfma_f32_16x16x32_bf16 v[8:11], v[180:183], v[226:229], v[8:11]
	v_mfma_f32_16x16x32_bf16 v[12:15], v[180:183], v[230:233], v[12:15]
	v_mfma_f32_16x16x32_bf16 v[16:19], v[180:183], v[234:237], v[16:19]
	v_mfma_f32_16x16x32_bf16 v[20:23], v[180:183], v[238:241], v[20:23]
	v_mfma_f32_16x16x32_bf16 v[24:27], v[180:183], v[242:245], v[24:27]
	v_mfma_f32_16x16x32_bf16 v[28:31], v[180:183], v[246:249], v[28:31]
	ds_read_b128 v[180:183], v215 offset:40960
	s_waitcnt lgkmcnt(3)
	v_mfma_f32_16x16x32_bf16 v[32:35], v[200:203], v[204:207], v[32:35]
	ds_read_b128 v[204:207], v197 offset:36864
	v_mfma_f32_16x16x32_bf16 v[36:39], v[200:203], v[222:225], v[36:39]
	ds_read_b128 v[222:225], v197 offset:38912
	v_mfma_f32_16x16x32_bf16 v[40:43], v[200:203], v[226:229], v[40:43]
	ds_read_b128 v[226:229], v197 offset:40960
	v_mfma_f32_16x16x32_bf16 v[44:47], v[200:203], v[230:233], v[44:47]
	ds_read_b128 v[230:233], v197 offset:43008
	v_mfma_f32_16x16x32_bf16 v[48:51], v[200:203], v[234:237], v[48:51]
	ds_read_b128 v[234:237], v197 offset:45056
	v_mfma_f32_16x16x32_bf16 v[52:55], v[200:203], v[238:241], v[52:55]
	ds_read_b128 v[238:241], v197 offset:47104
	v_mfma_f32_16x16x32_bf16 v[56:59], v[200:203], v[242:245], v[56:59]
	ds_read_b128 v[242:245], v197 offset:49152
	v_mfma_f32_16x16x32_bf16 v[60:63], v[200:203], v[246:249], v[60:63]
	ds_read_b128 v[246:249], v197 offset:51200
	ds_read_b128 v[200:203], v215 offset:43008
	s_waitcnt lgkmcnt(8)
	v_mfma_f32_16x16x32_bf16 v[64:67], v[160:163], v[204:207], v[64:67]
	s_waitcnt lgkmcnt(7)
	v_mfma_f32_16x16x32_bf16 v[68:71], v[160:163], v[222:225], v[68:71]
	s_waitcnt lgkmcnt(6)
	v_mfma_f32_16x16x32_bf16 v[72:75], v[160:163], v[226:229], v[72:75]
	s_waitcnt lgkmcnt(5)
	v_mfma_f32_16x16x32_bf16 v[76:79], v[160:163], v[230:233], v[76:79]
	s_waitcnt lgkmcnt(4)
	v_mfma_f32_16x16x32_bf16 v[80:83], v[160:163], v[234:237], v[80:83]
	s_waitcnt lgkmcnt(3)
	v_mfma_f32_16x16x32_bf16 v[84:87], v[160:163], v[238:241], v[84:87]
	s_waitcnt lgkmcnt(2)
	v_mfma_f32_16x16x32_bf16 v[88:91], v[160:163], v[242:245], v[88:91]
	s_waitcnt lgkmcnt(1)
	v_mfma_f32_16x16x32_bf16 v[92:95], v[160:163], v[246:249], v[92:95]
	v_mfma_f32_16x16x32_bf16 v[96:99], v[176:179], v[204:207], v[96:99]
	v_mfma_f32_16x16x32_bf16 v[100:103], v[176:179], v[222:225], v[100:103]
	v_mfma_f32_16x16x32_bf16 v[104:107], v[176:179], v[226:229], v[104:107]
	v_mfma_f32_16x16x32_bf16 v[108:111], v[176:179], v[230:233], v[108:111]
	v_mfma_f32_16x16x32_bf16 v[112:115], v[176:179], v[234:237], v[112:115]
	v_mfma_f32_16x16x32_bf16 v[116:119], v[176:179], v[238:241], v[116:119]
	v_mfma_f32_16x16x32_bf16 v[120:123], v[176:179], v[242:245], v[120:123]
	v_mfma_f32_16x16x32_bf16 v[124:127], v[176:179], v[246:249], v[124:127]
	v_mfma_f32_16x16x32_bf16 v[0:3], v[180:183], v[204:207], v[0:3]
	v_mfma_f32_16x16x32_bf16 v[4:7], v[180:183], v[222:225], v[4:7]
	v_mfma_f32_16x16x32_bf16 v[8:11], v[180:183], v[226:229], v[8:11]
	v_mfma_f32_16x16x32_bf16 v[12:15], v[180:183], v[230:233], v[12:15]
	v_mfma_f32_16x16x32_bf16 v[16:19], v[180:183], v[234:237], v[16:19]
	v_mfma_f32_16x16x32_bf16 v[20:23], v[180:183], v[238:241], v[20:23]
	v_mfma_f32_16x16x32_bf16 v[24:27], v[180:183], v[242:245], v[24:27]
	v_mfma_f32_16x16x32_bf16 v[28:31], v[180:183], v[246:249], v[28:31]
	s_waitcnt lgkmcnt(0)
	v_mfma_f32_16x16x32_bf16 v[32:35], v[200:203], v[204:207], v[32:35]
	v_mfma_f32_16x16x32_bf16 v[36:39], v[200:203], v[222:225], v[36:39]
	v_mfma_f32_16x16x32_bf16 v[40:43], v[200:203], v[226:229], v[40:43]
	v_mfma_f32_16x16x32_bf16 v[44:47], v[200:203], v[230:233], v[44:47]
	v_mfma_f32_16x16x32_bf16 v[48:51], v[200:203], v[234:237], v[48:51]
	v_mfma_f32_16x16x32_bf16 v[52:55], v[200:203], v[238:241], v[52:55]
	v_mfma_f32_16x16x32_bf16 v[56:59], v[200:203], v[242:245], v[56:59]
	v_mfma_f32_16x16x32_bf16 v[60:63], v[200:203], v[246:249], v[60:63]
	s_branch .Lgemm_kdone
.Lgemm_kloop_idle:
	s_waitcnt vmcnt(0) lgkmcnt(0)
	s_barrier
	s_add_u32 m0, s8, 0x0
	s_nop 0
	global_load_lds_dwordx4 v130, s[4:5]
	s_add_u32 m0, s8, 0x12000
	s_nop 0
	global_load_lds_dwordx4 v134, s[6:7]
	s_add_u32 m0, s8, 0x400
	s_nop 0
	global_load_lds_dwordx4 v131, s[4:5]
	s_add_u32 m0, s8, 0x12400
	s_nop 0
	global_load_lds_dwordx4 v135, s[6:7]
	s_add_u32 m0, s8, 0x800
	s_nop 0
	global_load_lds_dwordx4 v132, s[4:5]
	s_add_u32 m0, s8, 0x12800
	s_nop 0
	global_load_lds_dwordx4 v136, s[6:7]
	s_add_u32 m0, s8, 0xc00
	s_nop 0
	global_load_lds_dwordx4 v133, s[4:5]
	s_add_u32 m0, s8, 0x12c00
	s_nop 0
	global_load_lds_dwordx4 v137, s[6:7]
	s_add_u32 s4, s4, 0x80
	s_addc_u32 s5, s5, 0
	s_add_u32 s6, s6, 0x80
	s_addc_u32 s7, s7, 0
	s_waitcnt vmcnt(0) lgkmcnt(0)
	s_barrier
	s_add_u32 m0, s8, 0x9000
	s_nop 0
	global_load_lds_dwordx4 v130, s[4:5]
	s_add_u32 m0, s8, 0x1b000
	s_nop 0
	global_load_lds_dwordx4 v134, s[6:7]
	s_add_u32 m0, s8, 0x9400
	s_nop 0
	global_load_lds_dwordx4 v131, s[4:5]
	s_add_u32 m0, s8, 0x1b400
	s_nop 0
	global_load_lds_dwordx4 v135, s[6:7]
	s_add_u32 m0, s8, 0x9800
	s_nop 0
	global_load_lds_dwordx4 v132, s[4:5]
	s_add_u32 m0, s8, 0x1b800
	s_nop 0
	global_load_lds_dwordx4 v136, s[6:7]
	s_add_u32 m0, s8, 0x9c00
	s_nop 0
	global_load_lds_dwordx4 v133, s[4:5]
	s_add_u32 m0, s8, 0x1bc00
	s_nop 0
	global_load_lds_dwordx4 v137, s[6:7]
	s_add_u32 s4, s4, 0x80
	s_addc_u32 s5, s5, 0
	s_add_u32 s6, s6, 0x80
	s_addc_u32 s7, s7, 0
	s_add_i32 s1, s1, 2
	s_cmp_lt_i32 s1, s0
	s_cbranch_scc1 .Lgemm_kloop_idle
	s_waitcnt vmcnt(0) lgkmcnt(0)
	s_barrier
	s_branch .Lgemm_kdone
